# v10 + phase 0 tail: x->bf16 conversion on waves 0-3 and rope tables on waves 4-7 concurrently
# baseline (speedup 1.0000x reference)
.LBB0_78:
	v_and_b32_e32 v0, 0xff, v161
	v_lshl_add_u32 v0, s2, 8, v0
	s_mov_b32 s0, 0x200000
	s_lshl_b32 s4, s82, 8
	v_cmp_gt_i32_e32 vcc, s0, v0
	s_movk_i32 s23, 0x100
	v_cmp_gt_u32_e64 s[20:21], s23, v161
	v_ashrrev_i32_e32 v1, 31, v0
	v_lshlrev_b32_e32 v58, 1, v0
	s_nop 0
	s_and_b64 vcc, vcc, s[20:21]
	s_and_saveexec_b64 s[0:1], vcc
	v_readlane_b32 s48, v234, 7
	v_readlane_b32 s49, v234, 8
	v_readlane_b32 s50, v234, 9
	v_readlane_b32 s51, v234, 10
	v_readlane_b32 s52, v234, 11
	v_readlane_b32 s53, v234, 12
	v_readlane_b32 s54, v234, 13
	v_readlane_b32 s55, v234, 14
	v_readlane_b32 s56, v234, 15
	v_readlane_b32 s57, v234, 16
	v_readlane_b32 s58, v234, 17
	v_readlane_b32 s59, v234, 18
	v_readlane_b32 s60, v234, 19
	v_readlane_b32 s61, v234, 20
	v_readlane_b32 s62, v234, 21
	v_readlane_b32 s63, v234, 22
	s_cbranch_execz .LBB0_81
	v_lshl_add_u64 v[2:3], v[0:1], 4, s[84:85]
	s_mov_b64 s[6:7], 0xe400000
	s_ashr_i32 s5, s4, 31
	s_mov_b64 s[12:13], s[48:49]
	v_lshl_add_u64 v[2:3], v[2:3], 0, s[6:7]
	s_lshl_b64 s[6:7], s[4:5], 4
	v_lshlrev_b32_e32 v4, 1, v0
	s_lshl_b32 s5, s82, 9
	s_mov_b64 s[8:9], 0
	s_mov_b32 s10, 0x1fffff
	v_mov_b32_e32 v6, v0
	s_mul_i32 s11, s4, 3
	s_mov_b64 s[14:15], exec
	s_mov_b32 s16, 0x200000
	s_lshl_b32 s17, s4, 2
	s_lshl_b32 s20, s4, 3
	s_lshl_b64 s[18:19], s[6:7], 1

.LBB0_81:
	s_or_b64 exec, exec, s[0:1]
	s_mov_b32 s0, 0x80000
	v_cmp_gt_i32_e32 vcc, s0, v0
	s_movk_i32 s23, 0x100
	v_cmp_le_u32_e64 s[20:21], s23, v161
	s_nop 1
	s_and_b64 vcc, vcc, s[20:21]
	s_and_saveexec_b64 s[6:7], vcc
	s_cbranch_execz .LBB0_92
	v_lshl_add_u64 v[2:3], v[0:1], 2, s[84:85]
	s_mov_b64 s[0:1], 0x300000
	s_ashr_i32 s5, s4, 31
	s_mov_b32 s12, 0x55555555
	s_mov_b32 s14, 0x55555555
	s_mov_b32 s16, 0x4222de17
	s_mov_b32 s18, 0xfefa39ef
	s_mov_b32 s20, 0x3b39803f
	s_mov_b32 s24, 0x55555555
	s_mov_b32 s26, 0xd5df274d
	s_mov_b32 s28, 0
	s_mov_b32 s30, 0x652b82fe
	s_mov_b32 s38, 0x6a5dcb37
	s_mov_b32 s40, 0x11110bb3
	s_mov_b32 s44, 0x55555555
	s_mov_b32 s52, 0
	s_mov_b32 s58, 0x54442d18
	s_mov_b32 s68, 0x6dc9c883
	s_mov_b32 s70, 0x33145c00
	s_mov_b32 s72, 0x252049c0
	s_mov_b32 s74, 0x9037ab78
	s_mov_b32 s90, 0x46cc5e42
	s_mov_b32 s92, 0xa17f65f6
	s_mov_b32 s94, 0x19f4ec90
	s_mov_b32 s96, 0x16c16967
	s_mov_b32 s42, 0xb42fdfa7
	s_mov_b32 s48, 0xf9a43bb8
	s_mov_b32 s50, 0x796cde01
	s_mov_b32 s56, 0x19e83e5c
	v_lshl_add_u64 v[2:3], v[2:3], 0, s[0:1]
	s_lshl_b64 s[8:9], s[4:5], 2
	s_lshl_b32 s5, s82, 9
	s_mov_b64 s[10:11], 0
	v_mov_b32_e32 v1, 0x40c38800
	v_mov_b32_e32 v59, 0x3ff00000
	v_mov_b32_e32 v4, 0
	s_mov_b32 s13, 0x3fe55555
	s_mov_b32 s15, 0xbfc55555
	v_mov_b32_e32 v6, 0x968915a9
	v_mov_b32_e32 v7, 0x3fba6564
	s_mov_b32 s17, 0x3fbdee67
	v_mov_b32_e32 v8, 0x3abe935a
	v_mov_b32_e32 v9, 0x3fbe25e4
	v_mov_b32_e32 v10, 0x47e6c9c2
	v_mov_b32_e32 v11, 0x3fc110ef
	v_mov_b32_e32 v12, 0xcfa74449
	v_mov_b32_e32 v13, 0x3fc3b13b
	v_mov_b32_e32 v14, 0x71bf3c30
	v_mov_b32_e32 v15, 0x3fc745d1
	v_mov_b32_e32 v16, 0x1c7792ce
	v_mov_b32_e32 v17, 0x3fcc71c7
	v_mov_b32_e32 v18, 0x924920da
	v_mov_b32_e32 v19, 0x3fd24924
	v_mov_b32_e32 v20, 0x9999999c
	v_mov_b32_e32 v21, 0x3fd99999
	s_mov_b32 s19, 0x3fe62e42
	s_mov_b32 s21, 0x3c7abc9e
	s_mov_b32 s25, 0xbfe55555
	s_mov_b32 s27, 0x3c8543b0
	s_movk_i32 s23, 0x204
	s_mov_b32 s29, 0x7ff00000
	s_mov_b32 s31, 0x3ff71547
	s_mov_b32 s35, 0xbfe62e42
	s_mov_b32 s34, s18
	s_mov_b32 s37, 0xbc7abc9e
	s_mov_b32 s36, s20
	v_mov_b32_e32 v22, 0xfca7ab0c
	v_mov_b32_e32 v23, 0x3e928af3
	s_mov_b32 s39, 0x3e5ade15
	v_mov_b32_e32 v24, 0x623fde64
	v_mov_b32_e32 v25, 0x3ec71dee
	v_mov_b32_e32 v26, 0x7c89e6b0
	v_mov_b32_e32 v27, 0x3efa0199
	v_mov_b32_e32 v28, 0x14761f6e
	v_mov_b32_e32 v29, 0x3f2a01a0
	v_mov_b32_e32 v30, 0x1852b7b0
	v_mov_b32_e32 v31, 0x3f56c16c
	s_mov_b32 s41, 0x3f811111
	v_mov_b32_e32 v32, 0x11122322
	v_mov_b32_e32 v33, 0x3f811111
	s_mov_b32 s45, 0x3fa55555
	v_mov_b32_e32 v34, 0x555502a1
	v_mov_b32_e32 v35, 0x3fa55555
	v_mov_b32_e32 v36, 0x55555511
	v_mov_b32_e32 v37, 0x3fc55555
	v_mov_b32_e32 v38, 11
	v_mov_b32_e32 v39, 0x3fe00000
	v_mov_b32_e32 v60, 0x7ff00000
	s_mov_b32 s53, 0x7b000000
	s_mov_b32 s55, 0x3ff921fb
	s_mov_b32 s59, 0xbff921fb
	s_mov_b32 s61, 0x3c91a626
	s_mov_b32 s66, 0x33145c07
	s_mov_b32 s69, 0x3fe45f30
	s_mov_b32 s71, 0xbc91a626
	s_mov_b32 s73, 0xb97b839a
	s_mov_b32 s75, 0x3e21eeb6
	s_mov_b32 s91, 0xbda907db
	s_mov_b32 s93, 0xbe927e4f
	s_mov_b32 s95, 0x3efa01a0
	s_mov_b32 s97, 0xbf56c16c
	s_mov_b32 s43, 0xbe5ae600
	s_mov_b32 s49, 0x3de5e0b2
	s_mov_b32 s51, 0x3ec71de3
	s_mov_b32 s57, 0xbf2a01a0
	s_brev_b32 s88, 1
	v_mov_b32_e32 v61, 0x40100000
	v_mov_b32_e32 v62, 0x7ff80000
	s_branch .LBB0_84
